# waves 4-7 start the up-front weight conversion ~4us late so load and compute phases of the two wave halves interleave
# speedup vs baseline: 1.0050x; 1.0050x over previous
.LBB0_10:
	s_bitcmp1_b32 s2, 8
	s_cbranch_scc0 .Lnostag
	s_sleep 127
